# full-barrier leaders poll TOP with returning atomics (8 pollers), on stack20
# baseline (speedup 1.0000x reference)
; __device__ __forceinline__ unsigned xb_ld(unsigned* p)              { return __hip_atomic_load(p, __ATOMIC_RELAXED, __HIP_MEMORY_SCOPE_AGENT); }
; __device__ __forceinline__ unsigned xb_add(unsigned* p, unsigned v) { return __hip_atomic_fetch_add(p, v, __ATOMIC_RELAXED, __HIP_MEMORY_SCOPE_AGENT); }
; #define XB_SPIN(cond, bar) do { unsigned _sp = 0; while (cond) { __builtin_amdgcn_s_sleep(1); \
;     if ((++_sp & 255u) == 0u) { if (xb_ld(&(bar)[XB_TMO])) break; if (_sp > XB_SPIN_CAP) { atomicAdd(&(bar)[XB_TMO], 1u); break; } } } } while (0)
; __device__ __forceinline__ void xcd_barrier(const XcdBarrier& b) {
;     ...
;             const unsigned tg = og / nx;
;             if (og + 1u == (tg + 1u) * nx) xb_add(&bar[XB_TOPGEN], 1u);
;             else XB_SPIN(xb_ld(&bar[XB_TOPGEN]) == tg, bar);
;             __builtin_amdgcn_fence(__ATOMIC_ACQUIRE, "agent");
;             asm volatile("s_waitcnt vmcnt(0)" ::: "memory");
.Lxb_b1_spin:
	global_atomic_add v5, v177, v177, s[98:99] sc0
	s_waitcnt vmcnt(0)
	v_cmp_ge_u32_e32 vcc, v5, v4
	s_cbranch_vccnz .Lxb_b1_rel
	s_sleep 1
	s_add_i32 s100, s100, 1
	s_cmp_lt_u32 s100, 0x40000
	s_cbranch_scc1 .Lxb_b1_spin
